# attention ping-pong loops: first half reads the current K fragments from LDS before issuing the next tile's K/V requests (4 loops)
# speedup vs baseline: 1.0122x; 1.0022x over previous
.LBB0_498:
	s_waitcnt vmcnt(4)
	ds_read_b128 v[142:145], v234
	ds_read_b128 v[134:137], v235
	ds_read_b128 v[130:133], v236
	ds_read_b128 v[138:141], v237
	s_cmp_gt_i32 s45, -1
	s_cselect_b64 s[38:39], -1, 0
	s_cmp_lt_i32 s45, 0
	s_cselect_b32 s41, s44, s45
	s_lshl_b32 s41, s41, 5
	s_sub_i32 s41, s30, s41
	v_or_b32_e32 v0, s41, v175
	v_lshl_add_u32 v50, v0, 4, v162
	s_ashr_i32 s46, s41, 5
	s_ashr_i32 s47, s46, 31
	v_ashrrev_i32_e32 v51, 31, v50
	s_lshl_b64 s[46:47], s[46:47], 12
	v_lshl_add_u64 v[50:51], s[36:37], 0, v[50:51]
	v_lshl_add_u64 v[52:53], v[164:165], 0, s[46:47]
	v_mad_u64_u32 v[54:55], s[46:47], v50, s80, v[166:167]
	v_mad_i32_i24 v55, v51, s80, v55
	v_readfirstlane_b32 s100, v54
	v_readfirstlane_b32 s101, v55
	s_add_u32 m0, s98, 0x1000
	s_nop 4
	global_load_lds_dwordx4 v244, s[100:101]
	s_add_u32 m0, s98, 0x1400
	s_nop 0
	global_load_lds_dwordx4 v245, s[100:101]
	s_add_u32 m0, s98, 0x1800
	s_nop 0
	global_load_lds_dwordx4 v246, s[100:101]
	s_add_u32 m0, s98, 0x1c00
	s_nop 0
	global_load_lds_dwordx4 v247, s[100:101]
	v_and_b32_e32 v230, 63, v199
	v_lshlrev_b32_e32 v230, 4, v230
	v_sub_u32_e32 v230, 0, v230
	v_ashrrev_i32_e32 v231, 31, v230
	v_lshl_add_u64 v[230:231], v[52:53], 0, v[230:231]
	global_load_dwordx4 v[126:129], v[230:231], off
	global_load_dwordx4 v[122:125], v[230:231], off offset:1024
	global_load_dwordx4 v[118:121], v[230:231], off offset:2048
	global_load_dwordx4 v[114:117], v[230:231], off offset:3072
	s_waitcnt lgkmcnt(3)
	v_mfma_f32_32x32x16_bf16 v[34:49], v[142:145], v[82:85], 0
	v_or_b32_e32 v0, s40, v175
	v_add_u32_e32 v50, 0xffffff7f, v0
	v_cmp_gt_u32_e32 vcc, s2, v50
	s_waitcnt lgkmcnt(2)
	v_mfma_f32_32x32x16_bf16 v[34:49], v[134:137], v[86:89], v[34:49]
	s_waitcnt lgkmcnt(1)
	v_mfma_f32_32x32x16_bf16 v[34:49], v[130:133], v[90:93], v[34:49]
	s_waitcnt lgkmcnt(0)
	v_mfma_f32_32x32x16_bf16 v[34:49], v[138:141], v[94:97], v[34:49]
	s_cbranch_vccz .LBB0_500
	v_sub_u32_e32 v0, v163, v0
	v_cmp_gt_u32_e32 vcc, s3, v0
	v_add_u32_e32 v50, 0xffffff80, v0
	s_nop 7
	v_cndmask_b32_e32 v34, v212, v34, vcc
	v_cmp_lt_u32_e32 vcc, s8, v50
	v_add_u32_e32 v50, 0xffffff81, v0
	s_nop 0
	v_cndmask_b32_e32 v35, v212, v35, vcc
	v_cmp_lt_u32_e32 vcc, s8, v50
	v_add_u32_e32 v50, 0xffffff82, v0
	s_nop 0
	v_cndmask_b32_e32 v36, v212, v36, vcc
	v_cmp_lt_u32_e32 vcc, s8, v50
	v_add_u32_e32 v50, 0xffffff87, v0
	s_nop 0
	v_cndmask_b32_e32 v37, v212, v37, vcc
	v_cmp_lt_u32_e32 vcc, s8, v50
	v_add_u32_e32 v50, 0xffffff88, v0
	s_nop 0
	v_cndmask_b32_e32 v38, v212, v38, vcc
	v_cmp_lt_u32_e32 vcc, s8, v50
	v_add_u32_e32 v50, 0xffffff89, v0
	s_nop 0
	v_cndmask_b32_e32 v39, v212, v39, vcc
	v_cmp_lt_u32_e32 vcc, s8, v50
	v_add_u32_e32 v50, 0xffffff8a, v0
	s_nop 0
	v_cndmask_b32_e32 v40, v212, v40, vcc
	v_cmp_lt_u32_e32 vcc, s8, v50
	v_add_u32_e32 v50, 0xffffff8f, v0
	s_nop 0
	v_cndmask_b32_e32 v41, v212, v41, vcc
	v_cmp_lt_u32_e32 vcc, s8, v50
	v_add_u32_e32 v50, 0xffffff90, v0
	s_nop 0
	v_cndmask_b32_e32 v42, v212, v42, vcc
	v_cmp_lt_u32_e32 vcc, s8, v50
	v_add_u32_e32 v50, 0xffffff91, v0
	s_nop 0
	v_cndmask_b32_e32 v43, v212, v43, vcc
	v_cmp_lt_u32_e32 vcc, s8, v50
	v_add_u32_e32 v50, 0xffffff92, v0
	s_nop 0
	v_cndmask_b32_e32 v44, v212, v44, vcc
	v_cmp_lt_u32_e32 vcc, s8, v50
	v_add_u32_e32 v50, 0xffffff97, v0
	s_nop 0
	v_cndmask_b32_e32 v45, v212, v45, vcc
	v_cmp_lt_u32_e32 vcc, s8, v50
	v_add_u32_e32 v50, 0xffffff98, v0
	s_nop 0
	v_cndmask_b32_e32 v46, v212, v46, vcc
	v_cmp_lt_u32_e32 vcc, s8, v50
	v_add_u32_e32 v50, 0xffffff99, v0
	v_add_u32_e32 v0, 0xffffff9a, v0
	v_cndmask_b32_e32 v47, v212, v47, vcc
	v_cmp_lt_u32_e32 vcc, s8, v50
	s_nop 1
	v_cndmask_b32_e32 v48, v212, v48, vcc
	v_cmp_lt_u32_e32 vcc, s8, v0
	s_nop 1
	v_cndmask_b32_e32 v49, v212, v49, vcc

.LBB0_713:
	s_waitcnt vmcnt(4)
	ds_read_b128 v[142:145], v234
	ds_read_b128 v[134:137], v235
	ds_read_b128 v[126:129], v236
	ds_read_b128 v[138:141], v237
	s_cmp_gt_i32 s47, -1
	s_cselect_b64 s[38:39], -1, 0
	s_cmp_lt_i32 s47, 0
	s_cselect_b32 s41, s44, s47
	s_cmp_lt_i32 s41, 5
	s_cselect_b64 vcc, -1, 0
	s_and_b64 s[48:49], vcc, exec
	s_cselect_b32 s48, 0xffffff80, s83
	s_cselect_b32 s49, s43, s42
	s_lshl_b32 s41, s41, 5
	s_add_i32 s41, s48, s41
	v_mov_b32_e32 v0, s46
	s_add_i32 s41, s41, s49
	v_cndmask_b32_e32 v35, v0, v171, vcc
	v_or_b32_e32 v0, s41, v159
	v_lshl_add_u32 v36, v0, 2, v158
	s_ashr_i32 s48, s41, 5
	v_cndmask_b32_e32 v36, v0, v36, vcc
	s_ashr_i32 s49, s48, 31
	v_mov_b32_e32 v34, s45
	v_ashrrev_i32_e32 v37, 31, v36
	v_cndmask_b32_e32 v34, v34, v170, vcc
	s_lshl_b64 s[48:49], s[48:49], 12
	v_lshl_add_u64 v[52:53], s[0:1], 0, v[36:37]
	v_lshl_add_u64 v[34:35], v[34:35], 0, s[48:49]
	v_mad_u64_u32 v[54:55], s[48:49], v52, s80, v[174:175]
	v_lshlrev_b32_e32 v0, 1, v172
	v_mad_i32_i24 v55, v53, s80, v55
	v_lshl_add_u64 v[50:51], v[34:35], 0, v[0:1]
	v_readfirstlane_b32 s100, v54
	v_readfirstlane_b32 s101, v55
	s_add_u32 m0, s98, 0x1000
	s_nop 4
	global_load_lds_dwordx4 v244, s[100:101]
	s_add_u32 m0, s98, 0x1400
	s_nop 0
	global_load_lds_dwordx4 v245, s[100:101]
	s_add_u32 m0, s98, 0x1800
	s_nop 0
	global_load_lds_dwordx4 v246, s[100:101]
	s_add_u32 m0, s98, 0x1c00
	s_nop 0
	global_load_lds_dwordx4 v247, s[100:101]
	v_and_b32_e32 v230, 63, v199
	v_lshlrev_b32_e32 v230, 4, v230
	v_sub_u32_e32 v230, 0, v230
	v_ashrrev_i32_e32 v231, 31, v230
	v_lshl_add_u64 v[230:231], v[50:51], 0, v[230:231]
	global_load_dwordx4 v[130:133], v[230:231], off
	global_load_dwordx4 v[122:125], v[230:231], off offset:1024
	global_load_dwordx4 v[118:121], v[230:231], off offset:2048
	global_load_dwordx4 v[114:117], v[230:231], off offset:3072
	s_waitcnt lgkmcnt(3)
	v_mfma_f32_32x32x16_bf16 v[34:49], v[142:145], v[82:85], 0
	s_cmp_lt_u32 s44, 5
	s_cselect_b64 vcc, -1, 0
	s_and_b64 s[48:49], vcc, exec
	v_cndmask_b32_e32 v50, v166, v178, vcc
	s_cselect_b32 s41, 0x80, s58
	s_cselect_b32 s44, s43, s42
	v_add_u32_e32 v50, s41, v50
	s_waitcnt lgkmcnt(2)
	v_mfma_f32_32x32x16_bf16 v[34:49], v[134:137], v[86:89], v[34:49]
	s_add_i32 s40, s40, s44
	v_subrev_u32_e32 v50, s40, v50
	v_add_u32_e32 v51, 0xffffff7f, v50
	v_cmp_gt_u32_e32 vcc, s2, v51
	s_waitcnt lgkmcnt(1)
	v_mfma_f32_32x32x16_bf16 v[34:49], v[126:129], v[90:93], v[34:49]
	s_waitcnt lgkmcnt(0)
	v_mfma_f32_32x32x16_bf16 v[34:49], v[138:141], v[94:97], v[34:49]
	s_cbranch_vccz .LBB0_715
	v_sub_u32_e32 v50, v173, v50
	v_cmp_gt_u32_e32 vcc, s3, v50
	v_add_u32_e32 v51, 0xffffff80, v50
	s_nop 7
	v_cndmask_b32_e32 v34, v212, v34, vcc
	v_cmp_lt_u32_e32 vcc, s8, v51
	v_add_u32_e32 v51, 0xffffff81, v50
	s_nop 0
	v_cndmask_b32_e32 v35, v212, v35, vcc
	v_cmp_lt_u32_e32 vcc, s8, v51
	v_add_u32_e32 v51, 0xffffff82, v50
	s_nop 0
	v_cndmask_b32_e32 v36, v212, v36, vcc
	v_cmp_lt_u32_e32 vcc, s8, v51
	v_add_u32_e32 v51, 0xffffff87, v50
	s_nop 0
	v_cndmask_b32_e32 v37, v212, v37, vcc
	v_cmp_lt_u32_e32 vcc, s8, v51
	v_add_u32_e32 v51, 0xffffff88, v50
	s_nop 0
	v_cndmask_b32_e32 v38, v212, v38, vcc
	v_cmp_lt_u32_e32 vcc, s8, v51
	v_add_u32_e32 v51, 0xffffff89, v50
	s_nop 0
	v_cndmask_b32_e32 v39, v212, v39, vcc
	v_cmp_lt_u32_e32 vcc, s8, v51
	v_add_u32_e32 v51, 0xffffff8a, v50
	s_nop 0
	v_cndmask_b32_e32 v40, v212, v40, vcc
	v_cmp_lt_u32_e32 vcc, s8, v51
	v_add_u32_e32 v51, 0xffffff8f, v50
	s_nop 0
	v_cndmask_b32_e32 v41, v212, v41, vcc
	v_cmp_lt_u32_e32 vcc, s8, v51
	v_add_u32_e32 v51, 0xffffff90, v50
	s_nop 0
	v_cndmask_b32_e32 v42, v212, v42, vcc
	v_cmp_lt_u32_e32 vcc, s8, v51
	v_add_u32_e32 v51, 0xffffff91, v50
	s_nop 0
	v_cndmask_b32_e32 v43, v212, v43, vcc
	v_cmp_lt_u32_e32 vcc, s8, v51
	v_add_u32_e32 v51, 0xffffff92, v50
	s_nop 0
	v_cndmask_b32_e32 v44, v212, v44, vcc
	v_cmp_lt_u32_e32 vcc, s8, v51
	v_add_u32_e32 v51, 0xffffff97, v50
	s_nop 0
	v_cndmask_b32_e32 v45, v212, v45, vcc
	v_cmp_lt_u32_e32 vcc, s8, v51
	v_add_u32_e32 v51, 0xffffff98, v50
	s_nop 0
	v_cndmask_b32_e32 v46, v212, v46, vcc
	v_cmp_lt_u32_e32 vcc, s8, v51
	v_add_u32_e32 v51, 0xffffff99, v50
	v_add_u32_e32 v50, 0xffffff9a, v50
	v_cndmask_b32_e32 v47, v212, v47, vcc
	v_cmp_lt_u32_e32 vcc, s8, v51
	s_nop 1
	v_cndmask_b32_e32 v48, v212, v48, vcc
	v_cmp_lt_u32_e32 vcc, s8, v50
	s_nop 1
	v_cndmask_b32_e32 v49, v212, v49, vcc

.LBB0_764:
	s_waitcnt vmcnt(4)
	ds_read_b128 v[142:145], v234
	ds_read_b128 v[134:137], v235
	ds_read_b128 v[130:133], v236
	ds_read_b128 v[138:141], v237
	v_add_u32_e32 v0, 1, v184
	v_cmp_lt_i32_e32 vcc, v184, v159
	s_nop 1
	v_cndmask_b32_e32 v182, -1, v0, vcc
	v_cmp_gt_i32_e32 vcc, 0, v182
	s_nop 1
	v_cndmask_b32_e32 v50, v182, v184, vcc
	v_lshlrev_b32_e32 v34, 5, v50
	v_ashrrev_i32_e32 v35, 31, v34
	v_lshl_add_u64 v[52:53], v[174:175], 0, v[34:35]
	v_mad_u64_u32 v[54:55], s[40:41], v52, s80, v[178:179]
	v_mov_b32_e32 v0, v55
	v_mad_u64_u32 v[52:53], s[40:41], v53, s80, v[0:1]
	v_ashrrev_i32_e32 v51, 31, v50
	v_mov_b32_e32 v55, v52
	v_lshlrev_b64 v[50:51], 12, v[50:51]
	v_lshl_add_u64 v[50:51], v[176:177], 0, v[50:51]
	v_readfirstlane_b32 s100, v54
	v_readfirstlane_b32 s101, v55
	s_add_u32 m0, s98, 0x1000
	s_nop 4
	global_load_lds_dwordx4 v244, s[100:101]
	s_add_u32 m0, s98, 0x1400
	s_nop 0
	global_load_lds_dwordx4 v245, s[100:101]
	s_add_u32 m0, s98, 0x1800
	s_nop 0
	global_load_lds_dwordx4 v246, s[100:101]
	s_add_u32 m0, s98, 0x1c00
	s_nop 0
	global_load_lds_dwordx4 v247, s[100:101]
	v_and_b32_e32 v230, 63, v199
	v_lshlrev_b32_e32 v230, 4, v230
	v_sub_u32_e32 v230, 0, v230
	v_ashrrev_i32_e32 v231, 31, v230
	v_lshl_add_u64 v[230:231], v[50:51], 0, v[230:231]
	global_load_dwordx4 v[126:129], v[230:231], off
	global_load_dwordx4 v[122:125], v[230:231], off offset:1024
	global_load_dwordx4 v[118:121], v[230:231], off offset:2048
	global_load_dwordx4 v[114:117], v[230:231], off offset:3072
	s_waitcnt lgkmcnt(3)
	v_mfma_f32_32x32x16_bf16 v[34:49], v[142:145], v[94:97], 0
	v_cmp_lt_i32_e64 s[40:41], -1, v182
	s_waitcnt lgkmcnt(2)
	v_mfma_f32_32x32x16_bf16 v[34:49], v[134:137], v[86:89], v[34:49]
	s_waitcnt lgkmcnt(1)
	v_mfma_f32_32x32x16_bf16 v[34:49], v[130:133], v[82:85], v[34:49]
	s_waitcnt lgkmcnt(0)
	v_mfma_f32_32x32x16_bf16 v[34:49], v[138:141], v[90:93], v[34:49]
	s_nop 11
	v_max3_f32 v0, v34, v35, v36
	v_max3_f32 v50, v37, v38, v39
	v_max3_f32 v51, v40, v41, v42
	v_max3_f32 v52, v43, v44, v45
	v_max3_f32 v53, v46, v47, v48
	v_max3_f32 v0, v0, v50, v49
	v_max3_f32 v51, v51, v52, v53
	v_max_f32_e32 v0, v0, v51
	v_mov_b32_e32 v50, v0
	s_nop 1
	v_permlane32_swap_b32_e32 v0, v50
	v_max_f32_e32 v0, v0, v50
	v_add_f32_e32 v50, 0x41800000, v183
	v_cmp_gt_f32_e32 vcc, v0, v50
	s_cbranch_vccz .LBB0_766
	s_nop 0
	v_cndmask_b32_e32 v180, v183, v0, vcc
	v_sub_f32_e32 v0, v183, v180
	v_exp_f32_e32 v0, v0
	s_nop 0
	v_mul_f32_e32 v71, v71, v0
	v_pk_mul_f32 v[32:33], v[32:33], v[0:1] op_sel_hi:[1,0]
	v_pk_mul_f32 v[30:31], v[30:31], v[0:1] op_sel_hi:[1,0]
	v_pk_mul_f32 v[28:29], v[28:29], v[0:1] op_sel_hi:[1,0]
	v_pk_mul_f32 v[26:27], v[26:27], v[0:1] op_sel_hi:[1,0]
	v_pk_mul_f32 v[24:25], v[24:25], v[0:1] op_sel_hi:[1,0]
	v_pk_mul_f32 v[22:23], v[22:23], v[0:1] op_sel_hi:[1,0]
	v_pk_mul_f32 v[20:21], v[20:21], v[0:1] op_sel_hi:[1,0]
	v_pk_mul_f32 v[18:19], v[18:19], v[0:1] op_sel_hi:[1,0]
	v_pk_mul_f32 v[16:17], v[16:17], v[0:1] op_sel_hi:[1,0]
	v_pk_mul_f32 v[14:15], v[14:15], v[0:1] op_sel_hi:[1,0]
	v_pk_mul_f32 v[12:13], v[12:13], v[0:1] op_sel_hi:[1,0]
	v_pk_mul_f32 v[10:11], v[10:11], v[0:1] op_sel_hi:[1,0]
	v_pk_mul_f32 v[8:9], v[8:9], v[0:1] op_sel_hi:[1,0]
	v_pk_mul_f32 v[6:7], v[6:7], v[0:1] op_sel_hi:[1,0]
	v_pk_mul_f32 v[4:5], v[4:5], v[0:1] op_sel_hi:[1,0]
	v_pk_mul_f32 v[2:3], v[2:3], v[0:1] op_sel_hi:[1,0]
	s_branch .LBB0_767

.LBB0_854:
	s_waitcnt vmcnt(4)
	ds_read_b128 v[138:141], v234
	ds_read_b128 v[130:133], v235
	ds_read_b128 v[122:125], v236
	ds_read_b128 v[134:137], v237
	v_add_u32_e32 v34, 1, v190
	v_cmp_lt_i32_e32 vcc, v34, v162
	s_nop 1
	v_cndmask_b32_e32 v34, -1, v34, vcc
	v_cmp_eq_u32_e32 vcc, v190, v162
	s_nop 1
	v_cndmask_b32_e32 v71, v34, v188, vcc
	v_cmp_gt_i32_e64 s[0:1], 0, v71
	v_cmp_lt_i32_e64 s[38:39], -1, v71
	s_nop 0
	v_cndmask_b32_e64 v50, v71, v190, s[0:1]
	v_lshlrev_b32_e32 v34, 5, v50
	v_ashrrev_i32_e32 v35, 31, v34
	v_lshl_add_u64 v[52:53], v[168:169], 0, v[34:35]
	v_mad_u64_u32 v[54:55], s[0:1], v52, s80, v[170:171]
	v_mov_b32_e32 v52, v55
	v_mad_u64_u32 v[52:53], s[0:1], v53, s80, v[52:53]
	v_ashrrev_i32_e32 v51, 31, v50
	v_mov_b32_e32 v55, v52
	v_lshlrev_b64 v[50:51], 12, v[50:51]
	v_lshl_add_u64 v[50:51], v[166:167], 0, v[50:51]
	v_readfirstlane_b32 s100, v54
	v_readfirstlane_b32 s101, v55
	s_add_u32 m0, s98, 0x1000
	s_nop 4
	global_load_lds_dwordx4 v244, s[100:101]
	s_add_u32 m0, s98, 0x1400
	s_nop 0
	global_load_lds_dwordx4 v245, s[100:101]
	s_add_u32 m0, s98, 0x1800
	s_nop 0
	global_load_lds_dwordx4 v246, s[100:101]
	s_add_u32 m0, s98, 0x1c00
	s_nop 0
	global_load_lds_dwordx4 v247, s[100:101]
	v_and_b32_e32 v230, 63, v199
	v_lshlrev_b32_e32 v230, 4, v230
	v_sub_u32_e32 v230, 0, v230
	v_ashrrev_i32_e32 v231, 31, v230
	v_lshl_add_u64 v[230:231], v[50:51], 0, v[230:231]
	global_load_dwordx4 v[142:145], v[230:231], off
	global_load_dwordx4 v[126:129], v[230:231], off offset:1024
	global_load_dwordx4 v[118:121], v[230:231], off offset:2048
	global_load_dwordx4 v[114:117], v[230:231], off offset:3072
	s_waitcnt lgkmcnt(3)
	v_mfma_f32_32x32x16_bf16 v[34:49], v[138:141], v[90:93], 0
	v_cndmask_b32_e32 v50, v219, v187, vcc
	v_cmp_gt_u32_e32 vcc, s9, v50
	s_waitcnt lgkmcnt(2)
	v_mfma_f32_32x32x16_bf16 v[34:49], v[130:133], v[82:85], v[34:49]
	s_waitcnt lgkmcnt(1)
	v_mfma_f32_32x32x16_bf16 v[34:49], v[122:125], v[86:89], v[34:49]
	s_waitcnt lgkmcnt(0)
	v_mfma_f32_32x32x16_bf16 v[34:49], v[134:137], v[94:97], v[34:49]
	s_cbranch_vccz .LBB0_856
	v_cmp_le_u32_e32 vcc, v163, v50
	s_nop 9
	v_cndmask_b32_e32 v34, v212, v34, vcc
	v_cmp_le_u32_e32 vcc, v172, v50
	s_nop 1
	v_cndmask_b32_e32 v35, v212, v35, vcc
	v_cmp_le_u32_e32 vcc, v173, v50
	s_nop 1
	v_cndmask_b32_e32 v36, v212, v36, vcc
	v_cmp_le_u32_e32 vcc, v174, v50
	s_nop 1
	v_cndmask_b32_e32 v37, v212, v37, vcc
	v_cmp_le_u32_e32 vcc, v175, v50
	s_nop 1
	v_cndmask_b32_e32 v38, v212, v38, vcc
	v_cmp_le_u32_e32 vcc, v176, v50
	s_nop 1
	v_cndmask_b32_e32 v39, v212, v39, vcc
	v_cmp_le_u32_e32 vcc, v177, v50
	s_nop 1
	v_cndmask_b32_e32 v40, v212, v40, vcc
	v_cmp_le_u32_e32 vcc, v178, v50
	s_nop 1
	v_cndmask_b32_e32 v41, v212, v41, vcc
	v_cmp_le_u32_e32 vcc, v179, v50
	s_nop 1
	v_cndmask_b32_e32 v42, v212, v42, vcc
	v_cmp_le_u32_e32 vcc, v180, v50
	s_nop 1
	v_cndmask_b32_e32 v43, v212, v43, vcc
	v_cmp_le_u32_e32 vcc, v181, v50
	s_nop 1
	v_cndmask_b32_e32 v44, v212, v44, vcc
	v_cmp_le_u32_e32 vcc, v182, v50
	s_nop 1
	v_cndmask_b32_e32 v45, v212, v45, vcc
	v_cmp_le_u32_e32 vcc, v183, v50
	s_nop 1
	v_cndmask_b32_e32 v46, v212, v46, vcc
	v_cmp_le_u32_e32 vcc, v184, v50
	s_nop 1
	v_cndmask_b32_e32 v47, v212, v47, vcc
	v_cmp_le_u32_e32 vcc, v185, v50
	s_nop 1
	v_cndmask_b32_e32 v48, v212, v48, vcc
	v_cmp_le_u32_e32 vcc, v186, v50
	s_nop 1
	v_cndmask_b32_e32 v49, v212, v49, vcc
